# v72 + retention-out LDS read batching: K-fragment reads of the 8 QK blocks hoisted with counted lgkmcnt, V-fragment reads double-buffered
# baseline (speedup 1.0000x reference)
; #define LAS __attribute__((address_space(3)))
; #define GAS __attribute__((address_space(1)))
; #define MFMA16(a, b, c) __builtin_amdgcn_mfma_f32_16x16x32_bf16(a, b, c, 0, 0, 0)
; __device__ __forceinline__ void retout_items(LAS unsigned char* lds, const GAS bf16_t* proj, const GAS bf16_t* st, const GAS float* gnw, GAS bf16_t* mix, int q0, int qstride, int nit, int tid, int w, int lane) {
;     ...
;         f32x4 gnv[4];
; #pragma unroll
;         for (int et = 0; et < 4; ++et) gnv[et] = *(const GAS f32x4*)(gnw + 64 * h + 16 * et + 4 * fq);
;         f32x4 av, avm;
; #pragma unroll
;         for (int i = 0; i < 4; ++i) { const int d = fr - 4 * fq - i; const float e = __builtin_amdgcn_exp2f(lg2 * (float)d); av[i] = e; avm[i] = d >= 0 ? e : 0.f; }
;         f32x4 s[8];
; #pragma unroll
;         for (int kt = 0; kt < 8; ++kt) { s[kt] = (f32x4){0.f, 0.f, 0.f, 0.f};
;             if (kt <= w) {
; #pragma unroll
;                 for (int c = 0; c < 2; ++c) { const bf16x8 a = *(const LAS bf16x8*)(Ks + (16 * kt + fr) * KS + 32 * c + 8 * fq); s[kt] = MFMA16(a, qf[c], s[kt]); }
;                 if (kt == w) s[kt] = s[kt] * avm; else s[kt] = s[kt] * (av * __builtin_amdgcn_exp2f(lg2 * (float)(16 * (w - kt))));
;             } }
.LBB0_314:
	ds_read_b128 v[196:199], v193
	ds_read_b128 v[200:203], v193 offset:64
	ds_read_b128 v[204:207], v193 offset:2304
	ds_read_b128 v[208:211], v193 offset:2368
	ds_read_b128 v[212:215], v193 offset:4608
	ds_read_b128 v[216:219], v193 offset:4672
	ds_read_b128 v[228:231], v195
	ds_read_b128 v[234:237], v195 offset:64
	ds_read_b128 v[242:245], v193 offset:9216
	ds_read_b128 v[246:249], v193 offset:9280
	v_ldexp_f32 v30, v30, s8
	v_log_f32_e32 v30, v30
	s_lshl_b32 s8, s80, 6
	v_cndmask_b32_e32 v31, 0, v225, vcc
	s_ashr_i32 s9, s8, 31
	v_sub_f32_e32 v87, v30, v31
	v_lshl_add_u64 v[30:31], s[8:9], 2, v[78:79]
	global_load_dwordx4 v[50:53], v[30:31], off
	global_load_dwordx4 v[38:41], v[30:31], off offset:64
	global_load_dwordx4 v[34:37], v[30:31], off offset:128
	s_nop 0
	global_load_dwordx4 v[30:33], v[30:31], off offset:192
	v_mul_f32_e32 v54, v87, v138
	v_exp_f32_e32 v62, v54
	v_mul_f32_e32 v54, v87, v139
	v_exp_f32_e32 v63, v54
	v_mul_f32_e32 v54, v87, v140
	v_exp_f32_e32 v64, v54
	v_mul_f32_e32 v54, v87, v141
	v_exp_f32_e32 v65, v54
	v_cndmask_b32_e64 v54, 0, 1, s[26:27]
	v_mov_b32_e32 v102, 0
	v_cndmask_b32_e64 v58, 0, v62, s[0:1]
	v_cndmask_b32_e64 v59, 0, v63, s[2:3]
	v_cndmask_b32_e64 v60, 0, v64, s[4:5]
	v_cndmask_b32_e64 v61, 0, v65, s[6:7]
	v_cmp_ne_u32_e64 s[8:9], 1, v54
	s_andn2_b64 vcc, exec, s[26:27]
	v_mov_b32_e32 v106, 0
	v_mov_b32_e32 v107, 0
	v_mov_b32_e32 v104, 0
	v_mov_b32_e32 v105, 0
	s_cbranch_vccnz .LBB0_319
	s_mov_b64 s[10:11], -1
	s_and_b64 vcc, exec, s[28:29]
	s_waitcnt lgkmcnt(9)
	v_mfma_f32_16x16x32_bf16 v[54:57], v[196:199], v[42:45], 0
	s_waitcnt lgkmcnt(8)
	v_mfma_f32_16x16x32_bf16 v[54:57], v[200:203], v[46:49], v[54:57]
	s_cbranch_vccz .LBB0_317
	v_mul_f32_e32 v66, v87, v142
	v_exp_f32_e32 v66, v66
	s_mov_b64 s[10:11], 0
	v_pk_mul_f32 v[68:69], v[66:67], v[64:65] op_sel_hi:[0,1]
	v_pk_mul_f32 v[66:67], v[66:67], v[62:63] op_sel_hi:[0,1]
	s_nop 1
	v_pk_mul_f32 v[104:105], v[68:69], v[56:57]
	v_pk_mul_f32 v[106:107], v[66:67], v[54:55]

; #define LAS __attribute__((address_space(3)))
; #define MFMA16(a, b, c) __builtin_amdgcn_mfma_f32_16x16x32_bf16(a, b, c, 0, 0, 0)
; __device__ __forceinline__ void retout_items(LAS unsigned char* lds, const GAS bf16_t* proj, const GAS bf16_t* st, const GAS float* gnw, GAS bf16_t* mix, int q0, int qstride, int nit, int tid, int w, int lane) {
;     ...
;         for (int kt = 0; kt < 8; ++kt) { s[kt] = (f32x4){0.f, 0.f, 0.f, 0.f};
;             if (kt <= w) {
; #pragma unroll
;                 for (int c = 0; c < 2; ++c) { const bf16x8 a = *(const LAS bf16x8*)(Ks + (16 * kt + fr) * KS + 32 * c + 8 * fq); s[kt] = MFMA16(a, qf[c], s[kt]); }
;                 if (kt == w) s[kt] = s[kt] * avm; else s[kt] = s[kt] * (av * __builtin_amdgcn_exp2f(lg2 * (float)(16 * (w - kt))));
;             } }
.LBB0_319:
	s_andn2_b64 vcc, exec, s[52:53]
	v_mov_b32_e32 v103, 0
	v_mov_b32_e32 v114, 0
	v_mov_b32_e32 v115, 0
	s_cbranch_vccnz .LBB0_324
	s_andn2_b64 vcc, exec, s[54:55]
	s_mov_b64 s[10:11], -1
	s_waitcnt lgkmcnt(7)
	v_mfma_f32_16x16x32_bf16 v[54:57], v[204:207], v[42:45], 0
	s_waitcnt lgkmcnt(6)
	v_mfma_f32_16x16x32_bf16 v[54:57], v[208:211], v[46:49], v[54:57]
	s_cbranch_vccnz .LBB0_322
	v_mul_f32_e32 v66, v87, v143
	v_exp_f32_e32 v66, v66
	s_mov_b64 s[10:11], 0
	v_pk_mul_f32 v[68:69], v[66:67], v[64:65] op_sel_hi:[0,1]
	v_pk_mul_f32 v[66:67], v[66:67], v[62:63] op_sel_hi:[0,1]
	s_nop 1
	v_pk_mul_f32 v[114:115], v[68:69], v[56:57]
	v_pk_mul_f32 v[102:103], v[66:67], v[54:55]

; #define LAS __attribute__((address_space(3)))
; #define MFMA16(a, b, c) __builtin_amdgcn_mfma_f32_16x16x32_bf16(a, b, c, 0, 0, 0)
; __device__ __forceinline__ void retout_items(LAS unsigned char* lds, const GAS bf16_t* proj, const GAS bf16_t* st, const GAS float* gnw, GAS bf16_t* mix, int q0, int qstride, int nit, int tid, int w, int lane) {
;     ...
;         for (int kt = 0; kt < 8; ++kt) { s[kt] = (f32x4){0.f, 0.f, 0.f, 0.f};
;             if (kt <= w) {
; #pragma unroll
;                 for (int c = 0; c < 2; ++c) { const bf16x8 a = *(const LAS bf16x8*)(Ks + (16 * kt + fr) * KS + 32 * c + 8 * fq); s[kt] = MFMA16(a, qf[c], s[kt]); }
;                 if (kt == w) s[kt] = s[kt] * avm; else s[kt] = s[kt] * (av * __builtin_amdgcn_exp2f(lg2 * (float)(16 * (w - kt))));
;             } }
.LBB0_324:
	v_cndmask_b32_e64 v54, 0, 1, s[56:57]
	v_mov_b32_e32 v108, 0
	v_cmp_ne_u32_e64 s[10:11], 1, v54
	s_andn2_b64 vcc, exec, s[56:57]
	v_mov_b32_e32 v112, 0
	v_mov_b32_e32 v113, 0
	v_mov_b32_e32 v110, 0
	v_mov_b32_e32 v111, 0
	s_cbranch_vccnz .LBB0_329
	s_andn2_b64 vcc, exec, s[58:59]
	s_mov_b64 s[12:13], -1
	s_waitcnt lgkmcnt(5)
	v_mfma_f32_16x16x32_bf16 v[54:57], v[212:215], v[42:45], 0
	s_waitcnt lgkmcnt(4)
	v_mfma_f32_16x16x32_bf16 v[54:57], v[216:219], v[46:49], v[54:57]
	s_cbranch_vccnz .LBB0_327
	v_mul_f32_e32 v66, v87, v144
	v_exp_f32_e32 v66, v66
	s_mov_b64 s[12:13], 0
	v_pk_mul_f32 v[68:69], v[66:67], v[64:65] op_sel_hi:[0,1]
	v_pk_mul_f32 v[66:67], v[66:67], v[62:63] op_sel_hi:[0,1]
	s_nop 1
	v_pk_mul_f32 v[110:111], v[68:69], v[56:57]
	v_pk_mul_f32 v[112:113], v[66:67], v[54:55]

; #define LAS __attribute__((address_space(3)))
; #define MFMA16(a, b, c) __builtin_amdgcn_mfma_f32_16x16x32_bf16(a, b, c, 0, 0, 0)
; __device__ __forceinline__ void retout_items(LAS unsigned char* lds, const GAS bf16_t* proj, const GAS bf16_t* st, const GAS float* gnw, GAS bf16_t* mix, int q0, int qstride, int nit, int tid, int w, int lane) {
;     ...
;         for (int kt = 0; kt < 8; ++kt) { s[kt] = (f32x4){0.f, 0.f, 0.f, 0.f};
;             if (kt <= w) {
; #pragma unroll
;                 for (int c = 0; c < 2; ++c) { const bf16x8 a = *(const LAS bf16x8*)(Ks + (16 * kt + fr) * KS + 32 * c + 8 * fq); s[kt] = MFMA16(a, qf[c], s[kt]); }
;                 if (kt == w) s[kt] = s[kt] * avm; else s[kt] = s[kt] * (av * __builtin_amdgcn_exp2f(lg2 * (float)(16 * (w - kt))));
;             } }
.LBB0_329:
	ds_read_b128 v[196:199], v193 offset:11520
	ds_read_b128 v[200:203], v193 offset:11584
	ds_read_b128 v[204:207], v193 offset:13824
	ds_read_b128 v[208:211], v193 offset:13888
	ds_read_b128 v[212:215], v191
	ds_read_b128 v[216:219], v191 offset:64
	s_andn2_b64 vcc, exec, s[60:61]
	v_mov_b32_e32 v109, 0
	v_mov_b32_e32 v116, 0
	v_mov_b32_e32 v117, 0
	s_cbranch_vccnz .LBB0_334
	s_andn2_b64 vcc, exec, s[62:63]
	s_mov_b64 s[12:13], -1
	s_waitcnt lgkmcnt(9)
	v_mfma_f32_16x16x32_bf16 v[54:57], v[228:231], v[42:45], 0
	s_waitcnt lgkmcnt(8)
	v_mfma_f32_16x16x32_bf16 v[54:57], v[234:237], v[46:49], v[54:57]
	s_cbranch_vccnz .LBB0_332
	v_mul_f32_e32 v66, v87, v145
	v_exp_f32_e32 v66, v66
	s_mov_b64 s[12:13], 0
	v_pk_mul_f32 v[68:69], v[66:67], v[64:65] op_sel_hi:[0,1]
	v_pk_mul_f32 v[66:67], v[66:67], v[62:63] op_sel_hi:[0,1]
	s_nop 1
	v_pk_mul_f32 v[116:117], v[68:69], v[56:57]
	v_pk_mul_f32 v[108:109], v[66:67], v[54:55]

; #define LAS __attribute__((address_space(3)))
; #define MFMA16(a, b, c) __builtin_amdgcn_mfma_f32_16x16x32_bf16(a, b, c, 0, 0, 0)
; __device__ __forceinline__ void retout_items(LAS unsigned char* lds, const GAS bf16_t* proj, const GAS bf16_t* st, const GAS float* gnw, GAS bf16_t* mix, int q0, int qstride, int nit, int tid, int w, int lane) {
;     ...
;         for (int kt = 0; kt < 8; ++kt) { s[kt] = (f32x4){0.f, 0.f, 0.f, 0.f};
;             if (kt <= w) {
; #pragma unroll
;                 for (int c = 0; c < 2; ++c) { const bf16x8 a = *(const LAS bf16x8*)(Ks + (16 * kt + fr) * KS + 32 * c + 8 * fq); s[kt] = MFMA16(a, qf[c], s[kt]); }
;                 if (kt == w) s[kt] = s[kt] * avm; else s[kt] = s[kt] * (av * __builtin_amdgcn_exp2f(lg2 * (float)(16 * (w - kt))));
;             } }
.LBB0_334:
	v_cndmask_b32_e64 v54, 0, 1, s[64:65]
	v_mov_b32_e32 v118, 0
	v_cmp_ne_u32_e64 s[12:13], 1, v54
	s_andn2_b64 vcc, exec, s[64:65]
	v_mov_b32_e32 v122, 0
	v_mov_b32_e32 v123, 0
	v_mov_b32_e32 v120, 0
	v_mov_b32_e32 v121, 0
	s_cbranch_vccnz .LBB0_339
	s_andn2_b64 vcc, exec, s[66:67]
	s_mov_b64 s[14:15], -1
	s_waitcnt lgkmcnt(7)
	v_mfma_f32_16x16x32_bf16 v[54:57], v[242:245], v[42:45], 0
	s_waitcnt lgkmcnt(6)
	v_mfma_f32_16x16x32_bf16 v[54:57], v[246:249], v[46:49], v[54:57]
	s_cbranch_vccnz .LBB0_337
	v_mul_f32_e32 v66, v87, v146
	v_exp_f32_e32 v66, v66
	s_mov_b64 s[14:15], 0
	v_pk_mul_f32 v[68:69], v[66:67], v[64:65] op_sel_hi:[0,1]
	v_pk_mul_f32 v[66:67], v[66:67], v[62:63] op_sel_hi:[0,1]
	s_nop 1
	v_pk_mul_f32 v[120:121], v[68:69], v[56:57]
	v_pk_mul_f32 v[122:123], v[66:67], v[54:55]

; #define LAS __attribute__((address_space(3)))
; #define MFMA16(a, b, c) __builtin_amdgcn_mfma_f32_16x16x32_bf16(a, b, c, 0, 0, 0)
; __device__ __forceinline__ void retout_items(LAS unsigned char* lds, const GAS bf16_t* proj, const GAS bf16_t* st, const GAS float* gnw, GAS bf16_t* mix, int q0, int qstride, int nit, int tid, int w, int lane) {
;     ...
;         for (int kt = 0; kt < 8; ++kt) { s[kt] = (f32x4){0.f, 0.f, 0.f, 0.f};
;             if (kt <= w) {
; #pragma unroll
;                 for (int c = 0; c < 2; ++c) { const bf16x8 a = *(const LAS bf16x8*)(Ks + (16 * kt + fr) * KS + 32 * c + 8 * fq); s[kt] = MFMA16(a, qf[c], s[kt]); }
;                 if (kt == w) s[kt] = s[kt] * avm; else s[kt] = s[kt] * (av * __builtin_amdgcn_exp2f(lg2 * (float)(16 * (w - kt))));
;             } }
.LBB0_339:
	s_andn2_b64 vcc, exec, s[68:69]
	v_mov_b32_e32 v119, 0
	v_mov_b32_e32 v128, 0
	v_mov_b32_e32 v129, 0
	s_cbranch_vccnz .LBB0_344
	s_andn2_b64 vcc, exec, s[70:71]
	s_mov_b64 s[14:15], -1
	s_waitcnt lgkmcnt(5)
	v_mfma_f32_16x16x32_bf16 v[54:57], v[196:199], v[42:45], 0
	s_waitcnt lgkmcnt(4)
	v_mfma_f32_16x16x32_bf16 v[54:57], v[200:203], v[46:49], v[54:57]
	s_cbranch_vccnz .LBB0_342
	v_mul_f32_e32 v66, v87, v147
	v_exp_f32_e32 v66, v66
	s_mov_b64 s[14:15], 0
	v_pk_mul_f32 v[68:69], v[66:67], v[64:65] op_sel_hi:[0,1]
	v_pk_mul_f32 v[66:67], v[66:67], v[62:63] op_sel_hi:[0,1]
	s_nop 1
	v_pk_mul_f32 v[128:129], v[68:69], v[56:57]
	v_pk_mul_f32 v[118:119], v[66:67], v[54:55]

; #define LAS __attribute__((address_space(3)))
; #define MFMA16(a, b, c) __builtin_amdgcn_mfma_f32_16x16x32_bf16(a, b, c, 0, 0, 0)
; __device__ __forceinline__ void retout_items(LAS unsigned char* lds, const GAS bf16_t* proj, const GAS bf16_t* st, const GAS float* gnw, GAS bf16_t* mix, int q0, int qstride, int nit, int tid, int w, int lane) {
;     ...
;         for (int kt = 0; kt < 8; ++kt) { s[kt] = (f32x4){0.f, 0.f, 0.f, 0.f};
;             if (kt <= w) {
; #pragma unroll
;                 for (int c = 0; c < 2; ++c) { const bf16x8 a = *(const LAS bf16x8*)(Ks + (16 * kt + fr) * KS + 32 * c + 8 * fq); s[kt] = MFMA16(a, qf[c], s[kt]); }
;                 if (kt == w) s[kt] = s[kt] * avm; else s[kt] = s[kt] * (av * __builtin_amdgcn_exp2f(lg2 * (float)(16 * (w - kt))));
;             } }
.LBB0_344:
	v_cndmask_b32_e64 v54, 0, 1, s[72:73]
	v_mov_b32_e32 v124, 0
	v_cmp_ne_u32_e64 s[14:15], 1, v54
	s_andn2_b64 vcc, exec, s[72:73]
	v_mov_b32_e32 v130, 0
	v_mov_b32_e32 v131, 0
	v_mov_b32_e32 v126, 0
	v_mov_b32_e32 v127, 0
	s_cbranch_vccnz .LBB0_350
	s_andn2_b64 vcc, exec, s[74:75]
	s_mov_b64 s[82:83], -1
	s_waitcnt lgkmcnt(3)
	v_mfma_f32_16x16x32_bf16 v[54:57], v[204:207], v[42:45], 0
	s_waitcnt lgkmcnt(2)
	v_mfma_f32_16x16x32_bf16 v[54:57], v[208:211], v[46:49], v[54:57]
	s_cbranch_vccnz .LBB0_347
	v_mul_f32_e32 v66, v87, v148
	v_exp_f32_e32 v66, v66
	s_mov_b64 s[82:83], 0
	v_pk_mul_f32 v[68:69], v[66:67], v[64:65] op_sel_hi:[0,1]
	v_pk_mul_f32 v[66:67], v[66:67], v[62:63] op_sel_hi:[0,1]
	s_nop 1
	v_pk_mul_f32 v[126:127], v[68:69], v[56:57]
	v_pk_mul_f32 v[130:131], v[66:67], v[54:55]

; #define LAS __attribute__((address_space(3)))
; #define MFMA16(a, b, c) __builtin_amdgcn_mfma_f32_16x16x32_bf16(a, b, c, 0, 0, 0)
; __device__ __forceinline__ void retout_items(LAS unsigned char* lds, const GAS bf16_t* proj, const GAS bf16_t* st, const GAS float* gnw, GAS bf16_t* mix, int q0, int qstride, int nit, int tid, int w, int lane) {
;     ...
;         for (int kt = 0; kt < 8; ++kt) { s[kt] = (f32x4){0.f, 0.f, 0.f, 0.f};
;             if (kt <= w) {
; #pragma unroll
;                 for (int c = 0; c < 2; ++c) { const bf16x8 a = *(const LAS bf16x8*)(Ks + (16 * kt + fr) * KS + 32 * c + 8 * fq); s[kt] = MFMA16(a, qf[c], s[kt]); }
;                 if (kt == w) s[kt] = s[kt] * avm; else s[kt] = s[kt] * (av * __builtin_amdgcn_exp2f(lg2 * (float)(16 * (w - kt))));
;             } }
.LBB0_350:
	s_andn2_b64 vcc, exec, s[76:77]
	v_mov_b32_e32 v125, 0
	v_mov_b32_e32 v132, 0
	v_mov_b32_e32 v133, 0
	s_cbranch_vccnz .LBB0_356
	s_andn2_b64 vcc, exec, s[78:79]
	s_mov_b64 s[82:83], -1
	s_waitcnt lgkmcnt(1)
	v_mfma_f32_16x16x32_bf16 v[54:57], v[212:215], v[42:45], 0
	s_waitcnt lgkmcnt(0)
	v_mfma_f32_16x16x32_bf16 v[54:57], v[216:219], v[46:49], v[54:57]
	s_cbranch_vccnz .LBB0_353
	v_mul_f32_e32 v66, v87, v149
	v_exp_f32_e32 v66, v66
	s_mov_b64 s[82:83], 0
	v_pk_mul_f32 v[64:65], v[66:67], v[64:65] op_sel_hi:[0,1]
	v_pk_mul_f32 v[62:63], v[66:67], v[62:63] op_sel_hi:[0,1]
	s_nop 1
	v_pk_mul_f32 v[132:133], v[64:65], v[56:57]
	v_pk_mul_f32 v[124:125], v[62:63], v[54:55]

; __device__ __forceinline__ unsigned cvt_pk_bf16(float lo, float hi) { unsigned r; asm volatile("v_cvt_pk_bf16_f32 %0, %1, %2" : "=v"(r) : "v"(lo), "v"(hi)); return r; }
; #define LAS __attribute__((address_space(3)))
; __device__ __forceinline__ int tsw(int d) { return ((d >> 3) & 7) << 3; }
; #define MFMA16(a, b, c) __builtin_amdgcn_mfma_f32_16x16x32_bf16(a, b, c, 0, 0, 0)
; __device__ __forceinline__ void retout_items(LAS unsigned char* lds, const GAS bf16_t* proj, const GAS bf16_t* st, const GAS float* gnw, GAS bf16_t* mix, int q0, int qstride, int nit, int tid, int w, int lane) {
;     ...
;         for (int jj = 0; jj < 4; ++jj) {
;             if (2 * jj <= w) {
;                 u32x2 plo, phi; plo.x = cvt_pk_bf16(s[2 * jj][0], s[2 * jj][1]); plo.y = cvt_pk_bf16(s[2 * jj][2], s[2 * jj][3]);
;                 phi.x = cvt_pk_bf16(s[2 * jj + 1][0], s[2 * jj + 1][1]); phi.y = cvt_pk_bf16(s[2 * jj + 1][2], s[2 * jj + 1][3]);
;                 const bf16x8 pb = mk8(plo, phi);
; #pragma unroll
;                 for (int et = 0; et < 4; ++et) {
;                     const LAS bf16_t* vr = VTs + (16 * et + fr) * VS; const int sw = tsw(16 * et + fr), kc0 = 32 * jj + 4 * fq;
;                     const u32x2 a0 = *(const LAS u32x2*)(vr + (kc0 ^ sw)), a1 = *(const LAS u32x2*)(vr + ((kc0 + 16) ^ sw));
;                     o[et] = MFMA16(mk8(a0, a1), pb, o[et]);
;                 }
.LBB0_359:
	v_cvt_pk_bf16_f32 v70, v122, v123
	v_cvt_pk_bf16_f32 v71, v120, v121
	v_cvt_pk_bf16_f32 v72, v118, v119
	v_cvt_pk_bf16_f32 v73, v128, v129
	ds_read_b64 v[102:103], v166 offset:18432
	ds_read_b64 v[104:105], v167 offset:18432
	ds_read_b64 v[106:107], v168 offset:18432
	ds_read_b64 v[108:109], v169 offset:18432
	s_waitcnt lgkmcnt(2)
	v_mfma_f32_16x16x32_bf16 v[62:65], v[102:105], v[70:73], v[62:65]
	ds_read_b64 v[102:103], v170 offset:18432
	ds_read_b64 v[104:105], v171 offset:18432
	s_waitcnt lgkmcnt(2)
	v_mfma_f32_16x16x32_bf16 v[58:61], v[106:109], v[70:73], v[58:61]
	ds_read_b64 v[106:107], v172 offset:18432
	ds_read_b64 v[108:109], v173 offset:18432
	s_waitcnt lgkmcnt(2)
	v_mfma_f32_16x16x32_bf16 v[54:57], v[102:105], v[70:73], v[54:57]
	s_waitcnt lgkmcnt(0)
	v_mfma_f32_16x16x32_bf16 v[66:69], v[106:109], v[70:73], v[66:69]
	s_and_b64 vcc, exec, s[14:15]
	s_cbranch_vccnz .LBB0_311
	s_branch .LBB0_363

; __device__ __forceinline__ unsigned cvt_pk_bf16(float lo, float hi) { unsigned r; asm volatile("v_cvt_pk_bf16_f32 %0, %1, %2" : "=v"(r) : "v"(lo), "v"(hi)); return r; }
; #define LAS __attribute__((address_space(3)))
; __device__ __forceinline__ int tsw(int d) { return ((d >> 3) & 7) << 3; }
; #define MFMA16(a, b, c) __builtin_amdgcn_mfma_f32_16x16x32_bf16(a, b, c, 0, 0, 0)
; __device__ __forceinline__ void retout_items(LAS unsigned char* lds, const GAS bf16_t* proj, const GAS bf16_t* st, const GAS float* gnw, GAS bf16_t* mix, int q0, int qstride, int nit, int tid, int w, int lane) {
;     ...
;         for (int jj = 0; jj < 4; ++jj) {
;             if (2 * jj <= w) {
;                 u32x2 plo, phi; plo.x = cvt_pk_bf16(s[2 * jj][0], s[2 * jj][1]); plo.y = cvt_pk_bf16(s[2 * jj][2], s[2 * jj][3]);
;                 phi.x = cvt_pk_bf16(s[2 * jj + 1][0], s[2 * jj + 1][1]); phi.y = cvt_pk_bf16(s[2 * jj + 1][2], s[2 * jj + 1][3]);
;                 const bf16x8 pb = mk8(plo, phi);
; #pragma unroll
;                 for (int et = 0; et < 4; ++et) {
;                     const LAS bf16_t* vr = VTs + (16 * et + fr) * VS; const int sw = tsw(16 * et + fr), kc0 = 32 * jj + 4 * fq;
;                     const u32x2 a0 = *(const LAS u32x2*)(vr + (kc0 ^ sw)), a1 = *(const LAS u32x2*)(vr + ((kc0 + 16) ^ sw));
;                     o[et] = MFMA16(mk8(a0, a1), pb, o[et]);
;                 }
.LBB0_363:
	v_cvt_pk_bf16_f32 v70, v130, v131
	v_cvt_pk_bf16_f32 v71, v126, v127
	v_cvt_pk_bf16_f32 v72, v124, v125
	v_cvt_pk_bf16_f32 v73, v132, v133
	ds_read_b64 v[102:103], v174 offset:18432
	ds_read_b64 v[104:105], v175 offset:18432
	ds_read_b64 v[106:107], v176 offset:18432
	ds_read_b64 v[108:109], v177 offset:18432
	s_waitcnt lgkmcnt(2)
	v_mfma_f32_16x16x32_bf16 v[62:65], v[102:105], v[70:73], v[62:65]
	ds_read_b64 v[102:103], v186 offset:18432
	ds_read_b64 v[104:105], v187 offset:18432
	s_waitcnt lgkmcnt(2)
	v_mfma_f32_16x16x32_bf16 v[58:61], v[106:109], v[70:73], v[58:61]
	ds_read_b64 v[106:107], v188 offset:18432
	ds_read_b64 v[108:109], v189 offset:18432
	s_waitcnt lgkmcnt(2)
	v_mfma_f32_16x16x32_bf16 v[54:57], v[102:105], v[70:73], v[54:57]
	s_waitcnt lgkmcnt(0)
	v_mfma_f32_16x16x32_bf16 v[66:69], v[106:109], v[70:73], v[66:69]
	s_branch .LBB0_311
